# re-measure of the attention bias-fold version (same bytes as version 62)
# speedup vs baseline: 1.0015x; 1.0015x over previous
.LBB0_451:
	s_or_b64 exec, exec, s[2:3]
	v_add_co_u32_e32 v50, vcc, 0x1160000, v50
	v_lshl_add_u64 v[58:59], s[82:83], 0, v[42:43]
	s_nop 0
	v_addc_co_u32_e32 v51, vcc, 0, v51, vcc
	global_load_dwordx2 v[50:51], v[50:51], off offset:56
	v_add_co_u32_e32 v90, vcc, 0x1800000, v58
	v_cvt_pk_bf16_f32 v56, v72, v73
	v_cvt_pk_bf16_f32 v57, v74, v75
	s_nop 1
	v_addc_co_u32_e32 v91, vcc, 0, v59, vcc
	global_store_dwordx2 v[90:91], v[56:57], off nt
	s_and_saveexec_b64 s[2:3], s[6:7]
	s_cbranch_execz .LBB0_453
	v_add_co_u32_e32 v56, vcc, 0x1700000, v44
	s_nop 1
	v_addc_co_u32_e32 v57, vcc, 0, v45, vcc
	global_store_dwordx4 v[56:57], v[24:27], off

.LBB0_455:
	s_or_b64 exec, exec, s[2:3]
	s_waitcnt vmcnt(16)
	v_lshlrev_b32_e32 v90, 16, v82
	v_and_b32_e32 v91, 0xffff0000, v82
	s_waitcnt vmcnt(15)
	v_add_f32_e32 v84, v88, v84
	v_max_f32_e32 v82, v85, v85
	v_max_f32_e32 v82, v84, v82
	v_sub_f32_e32 v88, v84, v82
	v_sub_f32_e32 v84, v85, v82
	v_mul_f32_e32 v84, 0x3fb8aa3b, v84
	v_exp_f32_e32 v84, v84
	v_mul_f32_e32 v85, 0x3fb8aa3b, v88
	v_exp_f32_e32 v88, v85
	v_lshlrev_b32_e32 v92, 16, v83
	v_and_b32_e32 v93, 0xffff0000, v83
	v_pk_mul_f32 v[34:35], v[84:85], v[34:35] op_sel_hi:[0,1]
	v_pk_mul_f32 v[90:91], v[84:85], v[90:91] op_sel_hi:[0,1]
	v_pk_mul_f32 v[92:93], v[84:85], v[92:93] op_sel_hi:[0,1]
	v_pk_mul_f32 v[32:33], v[84:85], v[32:33] op_sel_hi:[0,1]
	v_pk_fma_f32 v[26:27], v[26:27], v[88:89], v[34:35] op_sel_hi:[1,0,1]
	v_add_co_u32_e32 v34, vcc, 0x1808000, v58
	v_pk_fma_f32 v[74:75], v[74:75], v[88:89], v[92:93] op_sel_hi:[1,0,1]
	v_pk_fma_f32 v[72:73], v[72:73], v[88:89], v[90:91] op_sel_hi:[1,0,1]
	v_pk_fma_f32 v[24:25], v[24:25], v[88:89], v[32:33] op_sel_hi:[1,0,1]
	v_addc_co_u32_e32 v35, vcc, 0, v59, vcc
	v_cvt_pk_bf16_f32 v32, v72, v73
	v_cvt_pk_bf16_f32 v33, v74, v75
	global_store_dwordx2 v[34:35], v[32:33], off nt
	s_and_saveexec_b64 s[2:3], s[6:7]
	s_cbranch_execz .LBB0_457
	v_add_co_u32_e32 v32, vcc, 0x1700000, v44
	s_nop 1
	v_addc_co_u32_e32 v33, vcc, 0, v45, vcc
	global_store_dwordx4 v[32:33], v[24:27], off offset:512

.LBB0_459:
	s_or_b64 exec, exec, s[2:3]
	s_waitcnt vmcnt(15)
	v_lshlrev_b32_e32 v32, 16, v78
	v_and_b32_e32 v33, 0xffff0000, v78
	s_waitcnt vmcnt(14)
	v_add_f32_e32 v35, v82, v80
	v_max_f32_e32 v78, v81, v81
	v_max_f32_e32 v78, v35, v78
	v_sub_f32_e32 v35, v35, v78
	v_sub_f32_e32 v80, v81, v78
	v_mul_f32_e32 v35, 0x3fb8aa3b, v35
	v_mul_f32_e32 v80, 0x3fb8aa3b, v80
	v_exp_f32_e32 v82, v35
	v_exp_f32_e32 v80, v80
	v_lshlrev_b32_e32 v34, 16, v79
	v_and_b32_e32 v35, 0xffff0000, v79
	v_pk_mul_f32 v[26:27], v[82:83], v[26:27] op_sel_hi:[0,1]
	v_pk_mul_f32 v[84:85], v[80:81], v[32:33] op_sel_hi:[0,1]
	v_pk_mul_f32 v[32:33], v[80:81], v[34:35] op_sel_hi:[0,1]
	v_pk_mul_f32 v[24:25], v[82:83], v[24:25] op_sel_hi:[0,1]
	v_pk_fma_f32 v[26:27], v[80:81], v[30:31], v[26:27] op_sel_hi:[0,1,1]
	v_add_co_u32_e32 v30, vcc, 0x1810000, v58
	v_pk_fma_f32 v[32:33], v[74:75], v[82:83], v[32:33] op_sel_hi:[1,0,1]
	v_pk_fma_f32 v[34:35], v[72:73], v[82:83], v[84:85] op_sel_hi:[1,0,1]
	v_pk_fma_f32 v[24:25], v[80:81], v[28:29], v[24:25] op_sel_hi:[0,1,1]
	v_addc_co_u32_e32 v31, vcc, 0, v59, vcc
	v_cvt_pk_bf16_f32 v28, v34, v35
	v_cvt_pk_bf16_f32 v29, v32, v33
	global_store_dwordx2 v[30:31], v[28:29], off nt
	s_and_saveexec_b64 s[2:3], s[6:7]
	s_cbranch_execz .LBB0_461
	v_add_co_u32_e32 v28, vcc, 0x1700000, v44
	s_nop 1
	v_addc_co_u32_e32 v29, vcc, 0, v45, vcc
	global_store_dwordx4 v[28:29], v[24:27], off offset:1024

.LBB0_463:
	s_or_b64 exec, exec, s[2:3]
	s_waitcnt vmcnt(14)
	v_lshlrev_b32_e32 v28, 16, v70
	v_and_b32_e32 v29, 0xffff0000, v70
	s_waitcnt vmcnt(13)
	v_add_f32_e32 v31, v78, v76
	v_max_f32_e32 v70, v77, v77
	v_max_f32_e32 v70, v31, v70
	v_sub_f32_e32 v31, v31, v70
	v_sub_f32_e32 v72, v77, v70
	v_mul_f32_e32 v31, 0x3fb8aa3b, v31
	v_mul_f32_e32 v72, 0x3fb8aa3b, v72
	v_exp_f32_e32 v74, v31
	v_exp_f32_e32 v72, v72
	v_lshlrev_b32_e32 v30, 16, v71
	v_and_b32_e32 v31, 0xffff0000, v71
	v_pk_mul_f32 v[26:27], v[74:75], v[26:27] op_sel_hi:[0,1]
	v_pk_mul_f32 v[76:77], v[72:73], v[28:29] op_sel_hi:[0,1]
	v_pk_mul_f32 v[28:29], v[72:73], v[30:31] op_sel_hi:[0,1]
	v_pk_mul_f32 v[24:25], v[74:75], v[24:25] op_sel_hi:[0,1]
	v_pk_fma_f32 v[18:19], v[72:73], v[18:19], v[26:27] op_sel_hi:[0,1,1]
	v_add_co_u32_e32 v26, vcc, 0x1818000, v58
	v_pk_fma_f32 v[28:29], v[32:33], v[74:75], v[28:29] op_sel_hi:[1,0,1]
	v_pk_fma_f32 v[30:31], v[34:35], v[74:75], v[76:77] op_sel_hi:[1,0,1]
	v_pk_fma_f32 v[16:17], v[72:73], v[16:17], v[24:25] op_sel_hi:[0,1,1]
	v_addc_co_u32_e32 v27, vcc, 0, v59, vcc
	v_cvt_pk_bf16_f32 v24, v30, v31
	v_cvt_pk_bf16_f32 v25, v28, v29
	global_store_dwordx2 v[26:27], v[24:25], off nt
	s_and_saveexec_b64 s[2:3], s[6:7]
	s_cbranch_execz .LBB0_465
	v_add_co_u32_e32 v24, vcc, 0x1700000, v44
	s_nop 1
	v_addc_co_u32_e32 v25, vcc, 0, v45, vcc
	global_store_dwordx4 v[24:25], v[16:19], off offset:1536

.LBB0_467:
	s_or_b64 exec, exec, s[2:3]
	s_waitcnt vmcnt(12)
	v_add_f32_e32 v27, v70, v68
	v_max_f32_e32 v32, v69, v69
	v_max_f32_e32 v32, v27, v32
	v_sub_f32_e32 v27, v27, v32
	v_sub_f32_e32 v33, v69, v32
	v_mul_f32_e32 v27, 0x3fb8aa3b, v27
	v_lshlrev_b32_e32 v24, 16, v66
	v_and_b32_e32 v25, 0xffff0000, v66
	v_mul_f32_e32 v33, 0x3fb8aa3b, v33
	v_exp_f32_e32 v66, v27
	v_exp_f32_e32 v34, v33
	v_lshlrev_b32_e32 v26, 16, v67
	v_and_b32_e32 v27, 0xffff0000, v67
	v_pk_mul_f32 v[18:19], v[66:67], v[18:19] op_sel_hi:[0,1]
	v_pk_mul_f32 v[68:69], v[34:35], v[24:25] op_sel_hi:[0,1]
	v_pk_mul_f32 v[24:25], v[34:35], v[26:27] op_sel_hi:[0,1]
	v_pk_mul_f32 v[16:17], v[66:67], v[16:17] op_sel_hi:[0,1]
	v_pk_fma_f32 v[18:19], v[34:35], v[22:23], v[18:19] op_sel_hi:[0,1,1]
	v_add_co_u32_e32 v22, vcc, 0x1820000, v58
	v_pk_fma_f32 v[24:25], v[28:29], v[66:67], v[24:25] op_sel_hi:[1,0,1]
	v_pk_fma_f32 v[26:27], v[30:31], v[66:67], v[68:69] op_sel_hi:[1,0,1]
	v_pk_fma_f32 v[16:17], v[34:35], v[20:21], v[16:17] op_sel_hi:[0,1,1]
	v_addc_co_u32_e32 v23, vcc, 0, v59, vcc
	v_cvt_pk_bf16_f32 v20, v26, v27
	v_cvt_pk_bf16_f32 v21, v24, v25
	global_store_dwordx2 v[22:23], v[20:21], off nt
	s_and_saveexec_b64 s[2:3], s[6:7]
	s_cbranch_execz .LBB0_469
	v_add_co_u32_e32 v20, vcc, 0x1700000, v44
	s_nop 1
	v_addc_co_u32_e32 v21, vcc, 0, v45, vcc
	global_store_dwordx4 v[20:21], v[16:19], off offset:2048

.LBB0_471:
	s_or_b64 exec, exec, s[2:3]
	s_waitcnt vmcnt(11)
	v_add_f32_e32 v23, v32, v64
	v_max_f32_e32 v28, v65, v65
	v_max_f32_e32 v28, v23, v28
	v_sub_f32_e32 v23, v23, v28
	v_sub_f32_e32 v29, v65, v28
	v_mul_f32_e32 v23, 0x3fb8aa3b, v23
	v_mul_f32_e32 v29, 0x3fb8aa3b, v29
	v_exp_f32_e32 v32, v23
	v_exp_f32_e32 v30, v29
	v_lshlrev_b32_e32 v20, 16, v62
	v_and_b32_e32 v21, 0xffff0000, v62
	v_lshlrev_b32_e32 v22, 16, v63
	v_and_b32_e32 v23, 0xffff0000, v63
	v_pk_mul_f32 v[18:19], v[32:33], v[18:19] op_sel_hi:[0,1]
	v_pk_mul_f32 v[34:35], v[30:31], v[20:21] op_sel_hi:[0,1]
	v_pk_mul_f32 v[20:21], v[30:31], v[22:23] op_sel_hi:[0,1]
	v_pk_mul_f32 v[16:17], v[32:33], v[16:17] op_sel_hi:[0,1]
	v_pk_fma_f32 v[10:11], v[30:31], v[10:11], v[18:19] op_sel_hi:[0,1,1]
	v_add_co_u32_e32 v18, vcc, 0x1828000, v58
	v_pk_fma_f32 v[20:21], v[24:25], v[32:33], v[20:21] op_sel_hi:[1,0,1]
	v_pk_fma_f32 v[22:23], v[26:27], v[32:33], v[34:35] op_sel_hi:[1,0,1]
	v_pk_fma_f32 v[8:9], v[30:31], v[8:9], v[16:17] op_sel_hi:[0,1,1]
	v_addc_co_u32_e32 v19, vcc, 0, v59, vcc
	v_cvt_pk_bf16_f32 v16, v22, v23
	v_cvt_pk_bf16_f32 v17, v20, v21
	global_store_dwordx2 v[18:19], v[16:17], off nt
	s_and_saveexec_b64 s[2:3], s[6:7]
	s_cbranch_execz .LBB0_473
	v_add_co_u32_e32 v16, vcc, 0x1700000, v44
	s_nop 1
	v_addc_co_u32_e32 v17, vcc, 0, v45, vcc
	global_store_dwordx4 v[16:17], v[8:11], off offset:2560

.LBB0_475:
	s_or_b64 exec, exec, s[2:3]
	s_waitcnt vmcnt(10)
	v_add_f32_e32 v19, v28, v60
	v_max_f32_e32 v24, v61, v61
	v_max_f32_e32 v24, v19, v24
	v_sub_f32_e32 v19, v19, v24
	v_sub_f32_e32 v25, v61, v24
	v_mul_f32_e32 v19, 0x3fb8aa3b, v19
	v_mul_f32_e32 v25, 0x3fb8aa3b, v25
	v_exp_f32_e32 v28, v19
	v_exp_f32_e32 v26, v25
	v_lshlrev_b32_e32 v16, 16, v54
	v_and_b32_e32 v17, 0xffff0000, v54
	v_lshlrev_b32_e32 v18, 16, v55
	v_and_b32_e32 v19, 0xffff0000, v55
	v_pk_mul_f32 v[10:11], v[28:29], v[10:11] op_sel_hi:[0,1]
	v_pk_mul_f32 v[30:31], v[26:27], v[16:17] op_sel_hi:[0,1]
	v_pk_mul_f32 v[16:17], v[26:27], v[18:19] op_sel_hi:[0,1]
	v_pk_mul_f32 v[8:9], v[28:29], v[8:9] op_sel_hi:[0,1]
	v_pk_fma_f32 v[10:11], v[26:27], v[14:15], v[10:11] op_sel_hi:[0,1,1]
	v_add_co_u32_e32 v14, vcc, 0x1830000, v58
	v_pk_fma_f32 v[16:17], v[20:21], v[28:29], v[16:17] op_sel_hi:[1,0,1]
	v_pk_fma_f32 v[18:19], v[22:23], v[28:29], v[30:31] op_sel_hi:[1,0,1]
	v_pk_fma_f32 v[8:9], v[26:27], v[12:13], v[8:9] op_sel_hi:[0,1,1]
	v_addc_co_u32_e32 v15, vcc, 0, v59, vcc
	v_cvt_pk_bf16_f32 v12, v18, v19
	v_cvt_pk_bf16_f32 v13, v16, v17
	global_store_dwordx2 v[14:15], v[12:13], off nt
	s_and_saveexec_b64 s[2:3], s[6:7]
	s_cbranch_execz .LBB0_477
	v_add_co_u32_e32 v12, vcc, 0x1700000, v44
	s_nop 1
	v_addc_co_u32_e32 v13, vcc, 0, v45, vcc
	global_store_dwordx4 v[12:13], v[8:11], off offset:3072

.LBB0_479:
	s_or_b64 exec, exec, s[2:3]
	s_waitcnt vmcnt(9)
	v_add_f32_e32 v15, v24, v52
	v_max_f32_e32 v20, v53, v53
	v_max_f32_e32 v20, v15, v20
	v_sub_f32_e32 v15, v15, v20
	v_sub_f32_e32 v21, v53, v20
	v_mul_f32_e32 v15, 0x3fb8aa3b, v15
	v_mul_f32_e32 v21, 0x3fb8aa3b, v21
	v_exp_f32_e32 v24, v15
	v_exp_f32_e32 v22, v21
	v_lshlrev_b32_e32 v12, 16, v48
	v_and_b32_e32 v13, 0xffff0000, v48
	v_lshlrev_b32_e32 v14, 16, v49
	v_and_b32_e32 v15, 0xffff0000, v49
	v_pk_mul_f32 v[10:11], v[24:25], v[10:11] op_sel_hi:[0,1]
	v_pk_mul_f32 v[26:27], v[22:23], v[12:13] op_sel_hi:[0,1]
	v_pk_mul_f32 v[12:13], v[22:23], v[14:15] op_sel_hi:[0,1]
	v_pk_mul_f32 v[8:9], v[24:25], v[8:9] op_sel_hi:[0,1]
	v_pk_fma_f32 v[2:3], v[22:23], v[2:3], v[10:11] op_sel_hi:[0,1,1]
	v_add_co_u32_e32 v10, vcc, 0x1838000, v58
	v_pk_fma_f32 v[12:13], v[16:17], v[24:25], v[12:13] op_sel_hi:[1,0,1]
	v_pk_fma_f32 v[14:15], v[18:19], v[24:25], v[26:27] op_sel_hi:[1,0,1]
	v_pk_fma_f32 v[0:1], v[22:23], v[0:1], v[8:9] op_sel_hi:[0,1,1]
	v_addc_co_u32_e32 v11, vcc, 0, v59, vcc
	v_cvt_pk_bf16_f32 v8, v14, v15
	v_cvt_pk_bf16_f32 v9, v12, v13
	global_store_dwordx2 v[10:11], v[8:9], off nt
	s_and_saveexec_b64 s[2:3], s[6:7]
	s_cbranch_execz .LBB0_481
	v_add_co_u32_e32 v8, vcc, 0x1700000, v44
	s_nop 1
	v_addc_co_u32_e32 v9, vcc, 0, v45, vcc
	global_store_dwordx4 v[8:9], v[0:3], off offset:3584
